# attention tile loops unrolled by 2 (even/odd LDS stage): loop-invariant LDS fragment address registers with static stage immediates
# speedup vs baseline: 1.0154x; 1.0154x over previous
; template <int DQK, bool MIXA, bool PIPE>
; DI void attn_item(const Params& P, int layer, char* smem, int b, int h, int qt) {
;     ...
;     for (int i = 0; i < DQK; ++i) { a1 = fmaxf(a1, fabsf(g1[i])); a2 = fmaxf(a2, fabsf(g2[i])); }
;     mfix = (float)DQK * 1.02f * a1 * a2 * sl2;
;     if (MIXA) {
;       const float b15 = P.rel_bias[15 * 8 + h];
;       float bm = 0.f;
;       for (int i = 0; i < 32; ++i) bm = fmaxf(bm, P.rel_bias[i * 8 + h] - b15);
;       mfix += bm * LOG2E;
;     }
;   }
;   if (MIXA) {
;     const int rel = tid - 192;
;     const float b15 = P.rel_bias[15 * 8 + h];
;     biasT[tid] = (P.rel_bias[t5_bucket(rel) * 8 + h] - b15) * LOG2E;
;   }
;   bf16x8 qf[NS];
; #pragma unroll
;   for (int s = 0; s < NS; ++s) qf[s] = *(const bf16x8*)(Qp + tokq * ldq + 16 * s + 8 * H);
;   const int nkt = 2 * qt + 2;
;   unsigned koff[NKI], voff[2];
; #pragma unroll
;   for (int i = 0; i < NKI; ++i) {
;     const int e = (w * NKI + i) * 64 + lane;
;     const int row = e / KCH, slot = e % KCH;
;     const int c = slot ^ (MIXA ? ((row >> 1) & 7) : ((row >> 2) & 3));
;     koff[i] = (unsigned)((row * ldk + c * 8) * 2);
;   }
; #pragma unroll
;   for (int i = 0; i < 2; ++i) {
;     const int e = (w * 2 + i) * 64 + lane;
;     const int row = e >> 3, slot = e & 7;
;     const int c = slot ^ ((row >> 1) & 7);
;     voff[i] = (unsigned)((row * S_ + c * 8) * 2);
;   }
;   unsigned mwn[2] = {0u, 0u};
;   auto issue_loads = [&](int kt) __attribute__((always_inline)) {
;     const char* kbp = (const char*)(Kp + (size_t)(kt * 64) * ldk);
;     const char* vbp = (const char*)(VT + kt * 64);
;     char* sk = smem + (kt & 1) * STG_B;
; #pragma unroll
;     for (int i = 0; i < NKI; ++i)
;       __builtin_amdgcn_global_load_lds((const unsigned*)(kbp + koff[i]), (unsigned*)(sk + (w * NKI + i) * 1024), 16, 0, 0);
; #pragma unroll
;     for (int i = 0; i < 2; ++i)
;       __builtin_amdgcn_global_load_lds((const unsigned*)(vbp + voff[i]), (unsigned*)(sk + KTILE_B + (w * 2 + i) * 1024), 16, 0, 0);
;     if (MIXA) {
;       if (kt <= cw) {
;         const unsigned* mp = mask + mask_base(b, cw) + (2 * kt) * 64 + (qpos & 63);
;         mwn[0] = mp[0]; mwn[1] = mp[64];
;       }
;     }
;   };
;   issue_loads(0);
;   f32x16 o[2];
; #pragma unroll
;   for (int d = 0; d < 2; ++d)
; #pragma unroll
;     for (int i = 0; i < 16; ++i) o[d][i] = 0.f;
;   float l = 0.f;
.LBB0_84:
	s_add_u32 s20, s65, s18
	s_addc_u32 s21, s66, s19
	global_load_dwordx4 v[4:7], v137, s[20:21] offset:32
	global_load_dwordx4 v[8:11], v137, s[20:21] offset:16
	global_load_dwordx4 v[12:15], v137, s[20:21]
	s_add_u32 s20, s67, s18
	s_addc_u32 s21, s68, s19
	global_load_dwordx4 v[16:19], v137, s[20:21]
	global_load_dwordx4 v[20:23], v137, s[20:21] offset:16
	global_load_dwordx4 v[24:27], v137, s[20:21] offset:32
	s_add_u32 s18, s18, 48
	s_addc_u32 s19, s19, 0
	s_cmpk_eq_i32 s18, 0x180
	s_waitcnt vmcnt(3)
	v_max3_f32 v2, v2, |v12|, |v13|
	s_waitcnt vmcnt(2)
	v_max3_f32 v1, v1, |v16|, |v17|
	v_max3_f32 v2, v2, |v14|, |v15|
	v_max3_f32 v1, v1, |v18|, |v19|
	v_max3_f32 v2, v2, |v8|, |v9|
	s_waitcnt vmcnt(1)
	v_max3_f32 v1, v1, |v20|, |v21|
	v_max3_f32 v2, v2, |v10|, |v11|
	v_max3_f32 v1, v1, |v22|, |v23|
	v_max3_f32 v2, v2, |v4|, |v5|
	s_waitcnt vmcnt(0)
	v_max3_f32 v1, v1, |v24|, |v25|
	v_max3_f32 v2, v2, |v6|, |v7|
	v_max3_f32 v1, v1, |v26|, |v27|
	s_cbranch_scc0 .LBB0_84
	v_lshl_or_b32 v3, v35, 3, s87
	v_ashrrev_i32_e32 v18, 6, v0
	v_mul_u32_u24_e32 v136, 0x300000, v3
	v_lshlrev_b32_e32 v3, 7, v34
	v_lshl_add_u32 v12, v18, 5, v3
	v_and_b32_e32 v20, 31, v0
	v_readlane_b32 s0, v252, 57
	v_or_b32_e32 v10, v12, v20
	v_lshlrev_b32_e32 v6, 14, v35
	v_readlane_b32 s1, v252, 58
	v_ashrrev_i32_e32 v11, 31, v10
	v_mov_b32_e32 v7, v137
	v_mul_f32_e32 v2, 0x42c3d70a, v2
	v_lshl_add_u64 v[8:9], s[0:1], 0, v[136:137]
	v_lshl_add_u64 v[112:113], v[10:11], 0, v[6:7]
	v_mul_f32_e32 v1, v1, v2
	v_mov_b64_e32 v[2:3], s[62:63]
	s_movk_i32 s0, 0x600
	v_bfe_u32 v139, v0, 5, 1
	v_mad_u64_u32 v[2:3], s[18:19], v112, s0, v[2:3]
	v_mad_i32_i24 v3, v113, s0, v3
	v_lshlrev_b32_e32 v6, 4, v139
	v_lshl_add_u64 v[2:3], v[2:3], 0, v[6:7]
	v_and_b32_e32 v21, 63, v0
	global_load_dwordx4 v[84:87], v[2:3], off
	global_load_dwordx4 v[80:83], v[2:3], off offset:32
	global_load_dwordx4 v[76:79], v[2:3], off offset:64
	global_load_dwordx4 v[72:75], v[2:3], off offset:96
	global_load_dwordx4 v[68:71], v[2:3], off offset:128
	global_load_dwordx4 v[64:67], v[2:3], off offset:160
	v_mul_lo_u32 v2, v18, s72
	v_or_b32_e32 v3, v2, v21
	s_mov_b32 s0, 0x2aaaaaab
	v_mul_hi_i32 v2, v3, s0
	v_lshrrev_b32_e32 v6, 31, v2
	v_ashrrev_i32_e32 v2, 1, v2
	v_add_u32_e32 v2, v2, v6
	v_mul_lo_u32 v6, v2, 12
	v_sub_u32_e32 v6, v3, v6
	v_lshrrev_b32_e32 v7, 2, v2
	v_bitop3_b32 v6, v7, v6, 3 bitop3:0x6c
	v_mul_lo_u32 v2, v2, s72
	v_lshl_add_u32 v2, v6, 4, v2
	v_add_u32_e32 v6, 64, v3
	v_mul_hi_i32 v7, v6, s0
	v_lshrrev_b32_e32 v10, 31, v7
	v_ashrrev_i32_e32 v7, 1, v7
	v_add_u32_e32 v7, v7, v10
	v_mul_lo_u32 v10, v7, 12
	v_sub_u32_e32 v6, v6, v10
	v_lshrrev_b32_e32 v10, 2, v7
	v_bitop3_b32 v6, v10, v6, 3 bitop3:0x6c
	v_mul_lo_u32 v7, v7, s72
	v_add_u32_e32 v3, 0x80, v3
	v_lshl_add_u32 v6, v6, 4, v7
	v_mul_hi_i32 v7, v3, s0
	v_lshrrev_b32_e32 v10, 31, v7
	v_ashrrev_i32_e32 v7, 1, v7
	v_add_u32_e32 v7, v7, v10
	v_mul_lo_u32 v10, v7, 12
	v_sub_u32_e32 v3, v3, v10
	v_lshrrev_b32_e32 v10, 2, v7
	v_bitop3_b32 v3, v10, v3, 3 bitop3:0x6c
	v_mul_lo_u32 v7, v7, s72
	v_lshl_add_u32 v10, v3, 4, v7
	v_mul_f32_e32 v114, 0x3e16c740, v1
	v_lshl_or_b32 v1, v18, 7, v21
	v_lshlrev_b32_e32 v3, 4, v0
	v_lshlrev_b32_e32 v7, 12, v1
	v_bitop3_b32 v22, v21, s92, v3 bitop3:0x48
	v_or_b32_e32 v1, 64, v1
	v_ashrrev_i32_e32 v127, 6, v12
	v_and_or_b32 v12, v7, s25, v22
	v_lshlrev_b32_e32 v7, 12, v1
	v_bitop3_b32 v1, v1, s92, v3 bitop3:0x48
	s_movk_i32 s0, 0x8000
	v_lshlrev_b32_e32 v19, 24, v35
	v_and_or_b32 v14, v7, s0, v1
	v_readlane_b32 s0, v252, 59
	v_or_b32_e32 v4, s88, v19
	v_mov_b32_e32 v5, v137
	v_readlane_b32 s1, v252, 60
	v_mov_b32_e32 v3, v137
	v_lshl_add_u64 v[16:17], v[8:9], 0, v[2:3]
	v_lshl_add_u64 v[4:5], s[0:1], 0, v[4:5]
	s_movk_i32 s0, 0xc00
	v_mul_lo_u32 v132, v18, s0
	v_add_u32_e32 v1, 0x400, v132
	v_readfirstlane_b32 s18, v132
	s_mov_b32 m0, s18
	v_mov_b32_e32 v7, v137
	v_readfirstlane_b32 s18, v1
	v_add_u32_e32 v1, 0x800, v132
	v_lshlrev_b32_e32 v135, 11, v18
	global_load_lds_dwordx4 v[16:17], off
	v_lshl_add_u64 v[16:17], v[8:9], 0, v[6:7]
	s_mov_b32 m0, s18
	v_mov_b32_e32 v11, v137
	v_readfirstlane_b32 s18, v1
	v_add_u32_e32 v1, 0x3000, v135
	global_load_lds_dwordx4 v[16:17], off
	v_lshl_add_u64 v[8:9], v[8:9], 0, v[10:11]
	s_mov_b32 m0, s18
	v_mov_b32_e32 v13, v137
	v_readfirstlane_b32 s18, v1
	v_add_u32_e32 v1, 0x3400, v135
	global_load_lds_dwordx4 v[8:9], off
	v_lshl_add_u64 v[8:9], v[4:5], 0, v[12:13]
	s_mov_b32 m0, s18
	v_mov_b32_e32 v15, v137
	v_readfirstlane_b32 s18, v1
	global_load_lds_dwordx4 v[8:9], off
	v_lshl_add_u64 v[4:5], v[4:5], 0, v[14:15]
	s_mov_b32 m0, s18
	v_and_b32_e32 v1, 19, v0
	global_load_lds_dwordx4 v[4:5], off
	v_lshlrev_b32_e32 v4, 1, v0
	v_lshrrev_b32_e32 v5, 1, v0
	v_and_b32_e32 v4, 8, v4
	v_and_b32_e32 v8, 4, v5
	v_or3_b32 v1, v4, v1, v8
	v_lshrrev_b32_e32 v4, 2, v1
	v_mul_u32_u24_e32 v141, 0xc0, v1
	v_or_b32_e32 v1, 2, v139
	v_bitop3_b32 v1, v4, v1, 3 bitop3:0x6c
	v_lshlrev_b32_e32 v142, 4, v1
	v_or_b32_e32 v1, 4, v139
	v_bitop3_b32 v1, v4, v1, 3 bitop3:0x6c
	v_lshlrev_b32_e32 v143, 4, v1
	v_or_b32_e32 v1, 6, v139
	v_bitop3_b32 v1, v4, v1, 3 bitop3:0x6c
	v_lshlrev_b32_e32 v144, 4, v1
	v_or_b32_e32 v1, 8, v139
	v_bitop3_b32 v1, v4, v1, 3 bitop3:0x6c
	v_lshlrev_b32_e32 v145, 4, v1
	v_or_b32_e32 v1, 10, v139
	v_bfe_u32 v0, v0, 1, 3
	v_bitop3_b32 v1, v4, v1, 3 bitop3:0x6c
	v_lshlrev_b32_e32 v146, 4, v1
	v_bitop3_b32 v1, v139, v0, 4 bitop3:0x36
	v_lshlrev_b32_e32 v130, 4, v1
	v_bitop3_b32 v1, v139, v5, 7 bitop3:0x78
	v_bitop3_b32 v8, v4, v139, 3 bitop3:0x6c
	v_lshlrev_b32_e32 v134, 4, v1
	v_bitop3_b32 v1, v139, v0, 2 bitop3:0x36
	v_bitop3_b32 v0, v139, v0, 6 bitop3:0x36
	v_lshlrev_b32_e32 v4, 12, v21
	s_waitcnt vmcnt(0)
; template <int DQK, bool MIXA, bool PIPE>
; DI void attn_item(const Params& P, int layer, char* smem, int b, int h, int qt) {
;     ...
;   issue_loads(0);
;   f32x16 o[2];
; #pragma unroll
;   for (int d = 0; d < 2; ++d)
; #pragma unroll
;     for (int i = 0; i < 16; ++i) o[d][i] = 0.f;
;   float l = 0.f;
;   const int pr = (l31 & ~12) | ((l31 & 4) << 1) | ((l31 & 8) >> 1);
;   const int swk = MIXA ? ((pr >> 1) & 7) : ((pr >> 2) & 3), swv = (l31 >> 1) & 7;
;   asm volatile("s_waitcnt vmcnt(0)" ::: "memory");
;   __syncthreads();
;   for (int kt = 0; kt < nkt; ++kt) {
	v_lshlrev_b32_e32 v133, 4, v1
	v_lshlrev_b32_e32 v131, 4, v0
	v_or_b32_e32 v0, s86, v19
	v_mov_b32_e32 v1, v137
	s_mov_b64 s[18:19], 0x1d000080
	v_lshl_or_b32 v4, v18, 19, v4
	v_lshlrev_b32_e32 v128, 1, v34
	v_lshl_add_u64 v[0:1], v[0:1], 0, s[18:19]
	v_and_or_b32 v4, v4, s25, v22
	v_mov_b32_e32 v5, v137
	v_or_b32_e32 v136, 0x18003000, v136
	v_mov_b32_e32 v126, 0
	v_lshlrev_b32_e32 v129, 7, v20
	v_mov_b32_e32 v115, v114
	v_sub_f32_e32 v228, 0, v114
	v_sub_f32_e32 v229, 0, v114
	v_sub_f32_e32 v230, 0, v114
	v_sub_f32_e32 v231, 0, v114
	v_sub_f32_e32 v232, 0, v114
	v_sub_f32_e32 v233, 0, v114
	v_sub_f32_e32 v234, 0, v114
	v_sub_f32_e32 v235, 0, v114
	v_sub_f32_e32 v236, 0, v114
	v_sub_f32_e32 v237, 0, v114
	v_sub_f32_e32 v238, 0, v114
	v_sub_f32_e32 v239, 0, v114
	v_sub_f32_e32 v240, 0, v114
	v_sub_f32_e32 v241, 0, v114
	v_sub_f32_e32 v242, 0, v114
	v_sub_f32_e32 v243, 0, v114
	v_lshlrev_b32_e32 v140, 4, v8
	v_or_b32_e32 v147, 1, v128
	v_lshl_add_u64 v[116:117], v[0:1], 0, v[4:5]
	v_lshl_add_u64 v[118:119], v[0:1], 0, v[14:15]
	s_mov_b32 s22, 0
	v_lshl_add_u64 v[120:121], v[136:137], 0, v[2:3]
	v_lshl_add_u64 v[122:123], v[136:137], 0, v[6:7]
	v_lshl_add_u64 v[124:125], v[136:137], 0, v[10:11]
	s_mov_b64 s[44:45], 0
	v_mov_b32_e32 v0, 0
	v_mov_b32_e32 v1, v126
	v_mov_b32_e32 v2, v126
	v_mov_b32_e32 v3, v126
	v_mov_b32_e32 v4, v126
	v_mov_b32_e32 v5, v126
	v_mov_b32_e32 v6, v126
	v_mov_b32_e32 v7, v126
	v_mov_b32_e32 v8, v126
	v_mov_b32_e32 v9, v126
	v_mov_b32_e32 v10, v126
	v_mov_b32_e32 v11, v126
	v_mov_b32_e32 v12, v126
	v_mov_b32_e32 v13, v126
	v_mov_b32_e32 v14, v126
	v_mov_b32_e32 v15, v126
	v_mov_b32_e32 v16, v126
	v_mov_b32_e32 v17, v126
	v_mov_b32_e32 v18, v126
	v_mov_b32_e32 v19, v126
	v_mov_b32_e32 v20, v126
	v_mov_b32_e32 v21, v126
	v_mov_b32_e32 v22, v126
	v_mov_b32_e32 v23, v126
	v_mov_b32_e32 v24, v126
	v_mov_b32_e32 v25, v126
	v_mov_b32_e32 v26, v126
	v_mov_b32_e32 v27, v126
	v_mov_b32_e32 v28, v126
	v_mov_b32_e32 v29, v126
	v_mov_b32_e32 v30, v126
	v_mov_b32_e32 v31, v126
	s_waitcnt vmcnt(0) lgkmcnt(0)
	s_barrier
	v_readfirstlane_b32 s32, v132
	v_readfirstlane_b32 s73, v135
	s_mov_b64 s[36:37], s[74:75]
	s_mov_b64 s[38:39], s[74:75]
	v_add_u32_e32 v168, v141, v140
	v_add_u32_e32 v170, v141, v142
	v_add_u32_e32 v172, v141, v143
	v_add_u32_e32 v174, v141, v144
	v_add_u32_e32 v176, v141, v145
	v_add_u32_e32 v244, v141, v146
	v_add_u32_e32 v245, v129, v134
	v_add_u32_e32 v246, v129, v133
	v_add_u32_e32 v247, v129, v130
	v_add_u32_e32 v248, v129, v131
	s_branch .LBB0_87

; template <int DQK, bool MIXA, bool PIPE>
; DI void attn_item(const Params& P, int layer, char* smem, int b, int h, int qt) {
;     ...
;     if (kt + 1 < nkt) issue_loads(kt + 1);
;     const char* Ks = smem + (kt & 1) * STG_B;
;     const char* Vs = Ks + KTILE_B;
;     if (kt <= cw) {
;       const int kc = kt;
;       bf16x8 kf[2][NS];
; #pragma unroll
;       for (int kb = 0; kb < 2; ++kb)
; #pragma unroll
;         for (int s = 0; s < NS; ++s) kf[kb][s] = *(const bf16x8*)(Ks + (32 * kb + pr) * KROWB + (((2 * s + H) ^ swk) << 4));
;       __builtin_amdgcn_sched_barrier(0);
;       f32x16 sacc[2];
; #pragma unroll
;       for (int kb = 0; kb < 2; ++kb)
; #pragma unroll
;         for (int i = 0; i < 16; ++i) sacc[kb][i] = 0.f;
; #pragma unroll
;       for (int s = 0; s < NS; ++s) sacc[0] = __builtin_amdgcn_mfma_f32_32x32x16_bf16(kf[0][s], qf[s], sacc[0], 0, 0, 0);
;       bf16x8 vf[2][2][2];
; #pragma unroll
;       for (int d = 0; d < 2; ++d)
; #pragma unroll
;         for (int kb = 0; kb < 2; ++kb)
; #pragma unroll
;           for (int s2 = 0; s2 < 2; ++s2)
;             vf[d][kb][s2] = *(const bf16x8*)(Vs + (d * 32 + l31) * 128 + (((4 * kb + 2 * s2 + H) ^ swv) << 4));
;     ...
;           sacc[1] = __builtin_amdgcn_mfma_f32_32x32x16_bf16(kf[1][s], qf[s], sacc[1], 0, 0, 0);
;           const int cend = (8 * (s + 1)) / NS;
; #pragma unroll
;           for (int c = 0; c < 8; ++c) if (c >= c0 && c < cend) chunk(0, c);
;           c0 = cend;
;           __builtin_amdgcn_sched_barrier(0);
;         }
;       }
;       bf16x8 pf0[2], pf1[2];
; #pragma unroll
;       for (int s2 = 0; s2 < 2; ++s2) { u32x4 t = {pkw[0][s2][0], pkw[0][s2][1], pkw[0][s2][2], pkw[0][s2][3]}; pf0[s2] = __builtin_bit_cast(bf16x8, t); }
; #pragma unroll
;       for (int j = 0; j < 4; ++j) {
;         const int s2 = j >> 1, d = j & 1;
;         o[d] = __builtin_amdgcn_mfma_f32_32x32x16_bf16(vf[d][0][s2], pf0[s2], o[d], 0, 0, 0);
;         chunk(1, 2 * j); chunk(1, 2 * j + 1);
;         __builtin_amdgcn_sched_barrier(0);
;       }
; #pragma unroll
;       for (int s2 = 0; s2 < 2; ++s2) { u32x4 t = {pkw[1][s2][0], pkw[1][s2][1], pkw[1][s2][2], pkw[1][s2][3]}; pf1[s2] = __builtin_bit_cast(bf16x8, t); }
; #pragma unroll
;       for (int j = 0; j < 4; ++j) {
;         const int s2 = j >> 1, d = j & 1;
;         o[d] = __builtin_amdgcn_mfma_f32_32x32x16_bf16(vf[d][1][s2], pf1[s2], o[d], 0, 0, 0);
;       }
.LBB0_87:
	s_add_i32 s20, s22, 1
	s_movk_i32 s21, 0x5000
	s_add_u32 m0, s21, s32
	s_add_u32 s18, s21, s73
	global_load_lds_dwordx4 v120, s[36:37]
	s_add_u32 m0, m0, 0x400
	s_nop 0
	global_load_lds_dwordx4 v122, s[36:37]
	s_add_u32 m0, m0, 0x400
	s_nop 0
	global_load_lds_dwordx4 v124, s[36:37]
	s_add_u32 m0, s18, 0x3000
	v_cmp_le_i32_e32 vcc, s22, v127
	global_load_lds_dwordx4 v116, s[38:39]
	s_add_u32 m0, s18, 0x3400
	s_nop 0
	global_load_lds_dwordx4 v118, s[38:39]
	s_and_saveexec_b64 s[18:19], vcc
	s_cbranch_execz .Lmla_o86
	ds_read_b128 v[32:35], v168
	ds_read_b128 v[36:39], v168 offset:6144
	ds_read_b128 v[40:43], v170
	ds_read_b128 v[148:151], v170 offset:6144
	ds_read_b128 v[44:47], v172
	ds_read_b128 v[152:155], v172 offset:6144
	ds_read_b128 v[88:91], v174
	ds_read_b128 v[156:159], v174 offset:6144
	ds_read_b128 v[92:95], v176
	ds_read_b128 v[208:211], v176 offset:6144
	ds_read_b128 v[96:99], v244
	ds_read_b128 v[212:215], v244 offset:6144
	s_waitcnt lgkmcnt(0)
	v_mfma_f32_32x32x16_bf16 v[48:63], v[32:35], v[84:87], v[228:243]
	ds_read_b128 v[216:219], v245 offset:12288
	ds_read_b128 v[108:111], v246 offset:12288
	v_mfma_f32_32x32x16_bf16 v[48:63], v[40:43], v[80:83], v[48:63]
	v_mfma_f32_32x32x16_bf16 v[48:63], v[44:47], v[76:79], v[48:63]
	v_mfma_f32_32x32x16_bf16 v[48:63], v[88:91], v[72:75], v[48:63]
	ds_read_b128 v[88:91], v247 offset:12288
	v_mfma_f32_32x32x16_bf16 v[48:63], v[92:95], v[68:71], v[48:63]
	v_mfma_f32_32x32x16_bf16 v[48:63], v[96:99], v[64:67], v[48:63]
	ds_read_b128 v[92:95], v248 offset:12288
	ds_read_b128 v[220:223], v245 offset:16384
	ds_read_b128 v[104:107], v246 offset:16384
	ds_read_b128 v[100:103], v247 offset:16384
	ds_read_b128 v[96:99], v248 offset:16384
	s_nop 6
	s_nop 0
	v_exp_f32_e32 v32, v62
	v_exp_f32_e32 v33, v63
	s_nop 0
	v_add_f32_e32 v224, 0, v32
	v_add_f32_e32 v225, 0, v33
	v_cvt_pk_bf16_f32 v63, v32, v33
	v_mfma_f32_32x32x16_bf16 v[32:47], v[36:39], v[84:87], v[228:243]
	v_mfma_f32_32x32x16_bf16 v[32:47], v[148:151], v[80:83], v[32:47]
	v_exp_f32_e32 v60, v60
	v_exp_f32_e32 v61, v61
	s_nop 0
	v_add_f32_e32 v224, v60, v224
	v_add_f32_e32 v225, v61, v225
	v_cvt_pk_bf16_f32 v62, v60, v61
	v_exp_f32_e32 v58, v58
	v_exp_f32_e32 v59, v59
	v_exp_f32_e32 v56, v56
	v_exp_f32_e32 v57, v57
	v_mfma_f32_32x32x16_bf16 v[32:47], v[152:155], v[76:79], v[32:47]
	v_add_f32_e64 v148, v58, v224
	v_add_f32_e64 v149, v59, v225
	v_cvt_pk_bf16_f32 v61, v58, v59
	v_add_f32_e64 v58, v56, v148
	v_add_f32_e64 v59, v57, v149
	v_cvt_pk_bf16_f32 v60, v56, v57
	v_mfma_f32_32x32x16_bf16 v[32:47], v[156:159], v[72:75], v[32:47]
	v_exp_f32_e32 v54, v54
	v_exp_f32_e32 v55, v55
	s_nop 0
	v_add_f32_e32 v56, v54, v58
	v_add_f32_e32 v57, v55, v59
	v_cvt_pk_bf16_f32 v55, v54, v55
	v_mfma_f32_32x32x16_bf16 v[32:47], v[208:211], v[68:71], v[32:47]
	v_exp_f32_e32 v52, v52
	v_exp_f32_e32 v53, v53
	s_nop 0
	v_add_f32_e32 v56, v52, v56
	v_add_f32_e32 v57, v53, v57
	v_cvt_pk_bf16_f32 v54, v52, v53
	v_exp_f32_e32 v50, v50
	v_exp_f32_e32 v51, v51
	v_exp_f32_e32 v48, v48
	v_exp_f32_e32 v49, v49
	v_mfma_f32_32x32x16_bf16 v[32:47], v[212:215], v[64:67], v[32:47]
	v_add_f32_e64 v56, v50, v56
	v_add_f32_e64 v57, v51, v57
	v_cvt_pk_bf16_f32 v53, v50, v51
	v_cvt_pk_bf16_f32 v52, v48, v49
	v_add_f32_e64 v48, v48, v56
	v_add_f32_e64 v49, v49, v57
	s_waitcnt lgkmcnt(0)
	v_mfma_f32_32x32x16_bf16 v[0:15], v[216:219], v[52:55], v[0:15]
	s_nop 3
	v_exp_f32_e32 v46, v46
	v_exp_f32_e32 v47, v47
	v_exp_f32_e32 v44, v44
	v_exp_f32_e32 v45, v45
	v_add_f32_e32 v48, v48, v46
	v_add_f32_e32 v49, v49, v47
	v_cvt_pk_bf16_f32 v47, v46, v47
	v_add_f32_e32 v48, v44, v48
	v_add_f32_e32 v49, v45, v49
	v_cvt_pk_bf16_f32 v46, v44, v45
	v_mfma_f32_32x32x16_bf16 v[16:31], v[220:223], v[52:55], v[16:31]
	v_exp_f32_e32 v42, v42
	v_exp_f32_e32 v43, v43
	v_exp_f32_e32 v40, v40
	v_exp_f32_e32 v41, v41
	v_add_f32_e32 v48, v42, v48
	v_add_f32_e32 v49, v43, v49
	v_cvt_pk_bf16_f32 v45, v42, v43
	v_add_f32_e32 v42, v40, v48
	v_add_f32_e32 v43, v41, v49
	v_cvt_pk_bf16_f32 v44, v40, v41
	v_mfma_f32_32x32x16_bf16 v[0:15], v[108:111], v[60:63], v[0:15]
	v_exp_f32_e32 v38, v38
	v_exp_f32_e32 v39, v39
	v_exp_f32_e32 v36, v36
	v_exp_f32_e32 v37, v37
	v_add_f32_e32 v40, v38, v42
	v_add_f32_e32 v41, v39, v43
	v_cvt_pk_bf16_f32 v39, v38, v39
	v_add_f32_e32 v40, v36, v40
	v_add_f32_e32 v41, v37, v41
	v_cvt_pk_bf16_f32 v38, v36, v37
	v_mfma_f32_32x32x16_bf16 v[16:31], v[104:107], v[60:63], v[16:31]
	v_exp_f32_e32 v34, v34
	v_exp_f32_e32 v35, v35
	v_exp_f32_e32 v32, v32
	v_exp_f32_e32 v33, v33
	v_cvt_pk_bf16_f32 v37, v34, v35
	v_cvt_pk_bf16_f32 v36, v32, v33
	s_nop 1
	v_mfma_f32_32x32x16_bf16 v[0:15], v[88:91], v[36:39], v[0:15]
	v_add_f32_e64 v34, v34, v40
	v_add_f32_e64 v35, v35, v41
	v_add_f32_e64 v32, v32, v34
	v_add_f32_e64 v33, v33, v35
	v_add_f32_e32 v32, v32, v33
	v_add_f32_e32 v126, v126, v32
	v_mfma_f32_32x32x16_bf16 v[16:31], v[100:103], v[36:39], v[16:31]
	v_mfma_f32_32x32x16_bf16 v[0:15], v[92:95], v[44:47], v[0:15]
	v_mfma_f32_32x32x16_bf16 v[16:31], v[96:99], v[44:47], v[16:31]
	s_branch .Lmla_o86

; template <int DQK, bool MIXA, bool PIPE>
; DI void attn_item(const Params& P, int layer, char* smem, int b, int h, int qt) {
;     ...
;     if (kt + 1 < nkt) issue_loads(kt + 1);
;     const char* Ks = smem + (kt & 1) * STG_B;
;     const char* Vs = Ks + KTILE_B;
;     if (kt <= cw) {
;       const int kc = kt;
;       bf16x8 kf[2][NS];
; #pragma unroll
;       for (int kb = 0; kb < 2; ++kb)
; #pragma unroll
;         for (int s = 0; s < NS; ++s) kf[kb][s] = *(const bf16x8*)(Ks + (32 * kb + pr) * KROWB + (((2 * s + H) ^ swk) << 4));
;       __builtin_amdgcn_sched_barrier(0);
;       f32x16 sacc[2];
; #pragma unroll
;       for (int kb = 0; kb < 2; ++kb)
; #pragma unroll
;         for (int i = 0; i < 16; ++i) sacc[kb][i] = 0.f;
; #pragma unroll
;       for (int s = 0; s < NS; ++s) sacc[0] = __builtin_amdgcn_mfma_f32_32x32x16_bf16(kf[0][s], qf[s], sacc[0], 0, 0, 0);
;       bf16x8 vf[2][2][2];
; #pragma unroll
;       for (int d = 0; d < 2; ++d)
; #pragma unroll
;         for (int kb = 0; kb < 2; ++kb)
; #pragma unroll
;           for (int s2 = 0; s2 < 2; ++s2)
;             vf[d][kb][s2] = *(const bf16x8*)(Vs + (d * 32 + l31) * 128 + (((4 * kb + 2 * s2 + H) ^ swv) << 4));
;     ...
;           sacc[1] = __builtin_amdgcn_mfma_f32_32x32x16_bf16(kf[1][s], qf[s], sacc[1], 0, 0, 0);
;           const int cend = (8 * (s + 1)) / NS;
; #pragma unroll
;           for (int c = 0; c < 8; ++c) if (c >= c0 && c < cend) chunk(0, c);
;           c0 = cend;
;           __builtin_amdgcn_sched_barrier(0);
;         }
;       }
;       bf16x8 pf0[2], pf1[2];
; #pragma unroll
;       for (int s2 = 0; s2 < 2; ++s2) { u32x4 t = {pkw[0][s2][0], pkw[0][s2][1], pkw[0][s2][2], pkw[0][s2][3]}; pf0[s2] = __builtin_bit_cast(bf16x8, t); }
; #pragma unroll
;       for (int j = 0; j < 4; ++j) {
;         const int s2 = j >> 1, d = j & 1;
;         o[d] = __builtin_amdgcn_mfma_f32_32x32x16_bf16(vf[d][0][s2], pf0[s2], o[d], 0, 0, 0);
;         chunk(1, 2 * j); chunk(1, 2 * j + 1);
;         __builtin_amdgcn_sched_barrier(0);
;       }
; #pragma unroll
;       for (int s2 = 0; s2 < 2; ++s2) { u32x4 t = {pkw[1][s2][0], pkw[1][s2][1], pkw[1][s2][2], pkw[1][s2][3]}; pf1[s2] = __builtin_bit_cast(bf16x8, t); }
; #pragma unroll
;       for (int j = 0; j < 4; ++j) {
;         const int s2 = j >> 1, d = j & 1;
;         o[d] = __builtin_amdgcn_mfma_f32_32x32x16_bf16(vf[d][1][s2], pf1[s2], o[d], 0, 0, 0);
;       }
.Lmla_o87:
	s_add_i32 s20, s22, 1
	s_mov_b32 s21, 0
	s_add_u32 m0, s21, s32
	s_add_u32 s18, s21, s73
	global_load_lds_dwordx4 v120, s[36:37]
	s_add_u32 m0, m0, 0x400
	s_nop 0
	global_load_lds_dwordx4 v122, s[36:37]
	s_add_u32 m0, m0, 0x400
	s_nop 0
	global_load_lds_dwordx4 v124, s[36:37]
	s_add_u32 m0, s18, 0x3000
	v_cmp_le_i32_e32 vcc, s22, v127
	global_load_lds_dwordx4 v116, s[38:39]
	s_add_u32 m0, s18, 0x3400
	s_nop 0
	global_load_lds_dwordx4 v118, s[38:39]
	s_and_saveexec_b64 s[18:19], vcc
	s_cbranch_execz .LBB0_86
	ds_read_b128 v[32:35], v168 offset:20480
	ds_read_b128 v[36:39], v168 offset:26624
	ds_read_b128 v[40:43], v170 offset:20480
	ds_read_b128 v[148:151], v170 offset:26624
	ds_read_b128 v[44:47], v172 offset:20480
	ds_read_b128 v[152:155], v172 offset:26624
	ds_read_b128 v[88:91], v174 offset:20480
	ds_read_b128 v[156:159], v174 offset:26624
	ds_read_b128 v[92:95], v176 offset:20480
	ds_read_b128 v[208:211], v176 offset:26624
	ds_read_b128 v[96:99], v244 offset:20480
	ds_read_b128 v[212:215], v244 offset:26624
	s_waitcnt lgkmcnt(0)
	v_mfma_f32_32x32x16_bf16 v[48:63], v[32:35], v[84:87], v[228:243]
	ds_read_b128 v[216:219], v245 offset:32768
	ds_read_b128 v[108:111], v246 offset:32768
	v_mfma_f32_32x32x16_bf16 v[48:63], v[40:43], v[80:83], v[48:63]
	v_mfma_f32_32x32x16_bf16 v[48:63], v[44:47], v[76:79], v[48:63]
	v_mfma_f32_32x32x16_bf16 v[48:63], v[88:91], v[72:75], v[48:63]
	ds_read_b128 v[88:91], v247 offset:32768
	v_mfma_f32_32x32x16_bf16 v[48:63], v[92:95], v[68:71], v[48:63]
	v_mfma_f32_32x32x16_bf16 v[48:63], v[96:99], v[64:67], v[48:63]
	ds_read_b128 v[92:95], v248 offset:32768
	ds_read_b128 v[220:223], v245 offset:36864
	ds_read_b128 v[104:107], v246 offset:36864
	ds_read_b128 v[100:103], v247 offset:36864
	ds_read_b128 v[96:99], v248 offset:36864
	s_nop 6
	s_nop 0
	v_exp_f32_e32 v32, v62
	v_exp_f32_e32 v33, v63
	s_nop 0
	v_add_f32_e32 v224, 0, v32
	v_add_f32_e32 v225, 0, v33
	v_cvt_pk_bf16_f32 v63, v32, v33
	v_mfma_f32_32x32x16_bf16 v[32:47], v[36:39], v[84:87], v[228:243]
	v_mfma_f32_32x32x16_bf16 v[32:47], v[148:151], v[80:83], v[32:47]
	v_exp_f32_e32 v60, v60
	v_exp_f32_e32 v61, v61
	s_nop 0
	v_add_f32_e32 v224, v60, v224
	v_add_f32_e32 v225, v61, v225
	v_cvt_pk_bf16_f32 v62, v60, v61
	v_exp_f32_e32 v58, v58
	v_exp_f32_e32 v59, v59
	v_exp_f32_e32 v56, v56
	v_exp_f32_e32 v57, v57
	v_mfma_f32_32x32x16_bf16 v[32:47], v[152:155], v[76:79], v[32:47]
	v_add_f32_e64 v148, v58, v224
	v_add_f32_e64 v149, v59, v225
	v_cvt_pk_bf16_f32 v61, v58, v59
	v_add_f32_e64 v58, v56, v148
	v_add_f32_e64 v59, v57, v149
	v_cvt_pk_bf16_f32 v60, v56, v57
	v_mfma_f32_32x32x16_bf16 v[32:47], v[156:159], v[72:75], v[32:47]
	v_exp_f32_e32 v54, v54
	v_exp_f32_e32 v55, v55
	s_nop 0
	v_add_f32_e32 v56, v54, v58
	v_add_f32_e32 v57, v55, v59
	v_cvt_pk_bf16_f32 v55, v54, v55
	v_mfma_f32_32x32x16_bf16 v[32:47], v[208:211], v[68:71], v[32:47]
	v_exp_f32_e32 v52, v52
	v_exp_f32_e32 v53, v53
	s_nop 0
	v_add_f32_e32 v56, v52, v56
	v_add_f32_e32 v57, v53, v57
	v_cvt_pk_bf16_f32 v54, v52, v53
	v_exp_f32_e32 v50, v50
	v_exp_f32_e32 v51, v51
	v_exp_f32_e32 v48, v48
	v_exp_f32_e32 v49, v49
	v_mfma_f32_32x32x16_bf16 v[32:47], v[212:215], v[64:67], v[32:47]
	v_add_f32_e64 v56, v50, v56
	v_add_f32_e64 v57, v51, v57
	v_cvt_pk_bf16_f32 v53, v50, v51
	v_cvt_pk_bf16_f32 v52, v48, v49
	v_add_f32_e64 v48, v48, v56
	v_add_f32_e64 v49, v49, v57
	s_waitcnt lgkmcnt(0)
	v_mfma_f32_32x32x16_bf16 v[0:15], v[216:219], v[52:55], v[0:15]
	s_nop 3
	v_exp_f32_e32 v46, v46
	v_exp_f32_e32 v47, v47
	v_exp_f32_e32 v44, v44
	v_exp_f32_e32 v45, v45
	v_add_f32_e32 v48, v48, v46
	v_add_f32_e32 v49, v49, v47
	v_cvt_pk_bf16_f32 v47, v46, v47
	v_add_f32_e32 v48, v44, v48
	v_add_f32_e32 v49, v45, v49
	v_cvt_pk_bf16_f32 v46, v44, v45
	v_mfma_f32_32x32x16_bf16 v[16:31], v[220:223], v[52:55], v[16:31]
	v_exp_f32_e32 v42, v42
	v_exp_f32_e32 v43, v43
	v_exp_f32_e32 v40, v40
	v_exp_f32_e32 v41, v41
	v_add_f32_e32 v48, v42, v48
	v_add_f32_e32 v49, v43, v49
	v_cvt_pk_bf16_f32 v45, v42, v43
	v_add_f32_e32 v42, v40, v48
	v_add_f32_e32 v43, v41, v49
	v_cvt_pk_bf16_f32 v44, v40, v41
	v_mfma_f32_32x32x16_bf16 v[0:15], v[108:111], v[60:63], v[0:15]
	v_exp_f32_e32 v38, v38
	v_exp_f32_e32 v39, v39
	v_exp_f32_e32 v36, v36
	v_exp_f32_e32 v37, v37
	v_add_f32_e32 v40, v38, v42
	v_add_f32_e32 v41, v39, v43
	v_cvt_pk_bf16_f32 v39, v38, v39
	v_add_f32_e32 v40, v36, v40
	v_add_f32_e32 v41, v37, v41
	v_cvt_pk_bf16_f32 v38, v36, v37
	v_mfma_f32_32x32x16_bf16 v[16:31], v[104:107], v[60:63], v[16:31]
	v_exp_f32_e32 v34, v34
	v_exp_f32_e32 v35, v35
	v_exp_f32_e32 v32, v32
	v_exp_f32_e32 v33, v33
	v_cvt_pk_bf16_f32 v37, v34, v35
	v_cvt_pk_bf16_f32 v36, v32, v33
	s_nop 1
	v_mfma_f32_32x32x16_bf16 v[0:15], v[88:91], v[36:39], v[0:15]
	v_add_f32_e64 v34, v34, v40
	v_add_f32_e64 v35, v35, v41
	v_add_f32_e64 v32, v32, v34
	v_add_f32_e64 v33, v33, v35
	v_add_f32_e32 v32, v32, v33
	v_add_f32_e32 v126, v126, v32
	v_mfma_f32_32x32x16_bf16 v[16:31], v[100:103], v[36:39], v[16:31]
	v_mfma_f32_32x32x16_bf16 v[0:15], v[92:95], v[44:47], v[0:15]
	v_mfma_f32_32x32x16_bf16 v[16:31], v[96:99], v[44:47], v[16:31]
	s_branch .LBB0_86

; template <int DQK, bool MIXA, bool PIPE>
; DI void attn_item(const Params& P, int layer, char* smem, int b, int h, int qt) {
;     ...
;     if (MIXA) {
;       const float b15 = P.rel_bias[15 * 8 + h];
;       float bm = 0.f;
;       for (int i = 0; i < 32; ++i) bm = fmaxf(bm, P.rel_bias[i * 8 + h] - b15);
;       mfix += bm * LOG2E;
;     }
;   }
;   if (MIXA) {
;     const int rel = tid - 192;
;     const float b15 = P.rel_bias[15 * 8 + h];
;     biasT[tid] = (P.rel_bias[t5_bucket(rel) * 8 + h] - b15) * LOG2E;
;   }
;   bf16x8 qf[NS];
; #pragma unroll
;   for (int s = 0; s < NS; ++s) qf[s] = *(const bf16x8*)(Qp + tokq * ldq + 16 * s + 8 * H);
;   const int nkt = 2 * qt + 2;
;   unsigned koff[NKI], voff[2];
; #pragma unroll
;   for (int i = 0; i < NKI; ++i) {
;     const int e = (w * NKI + i) * 64 + lane;
;     const int row = e / KCH, slot = e % KCH;
;     const int c = slot ^ (MIXA ? ((row >> 1) & 7) : ((row >> 2) & 3));
;     koff[i] = (unsigned)((row * ldk + c * 8) * 2);
;   }
; #pragma unroll
;   for (int i = 0; i < 2; ++i) {
;     const int e = (w * 2 + i) * 64 + lane;
;     const int row = e >> 3, slot = e & 7;
;     const int c = slot ^ ((row >> 1) & 7);
;     voff[i] = (unsigned)((row * S_ + c * 8) * 2);
;   }
;   unsigned mwn[2] = {0u, 0u};
;   auto issue_loads = [&](int kt) __attribute__((always_inline)) {
;     const char* kbp = (const char*)(Kp + (size_t)(kt * 64) * ldk);
;     const char* vbp = (const char*)(VT + kt * 64);
;     char* sk = smem + (kt & 1) * STG_B;
; #pragma unroll
;     for (int i = 0; i < NKI; ++i)
;       __builtin_amdgcn_global_load_lds((const unsigned*)(kbp + koff[i]), (unsigned*)(sk + (w * NKI + i) * 1024), 16, 0, 0);
; #pragma unroll
;     for (int i = 0; i < 2; ++i)
;       __builtin_amdgcn_global_load_lds((const unsigned*)(vbp + voff[i]), (unsigned*)(sk + KTILE_B + (w * 2 + i) * 1024), 16, 0, 0);
;     if (MIXA) {
;       if (kt <= cw) {
;         const unsigned* mp = mask + mask_base(b, cw) + (2 * kt) * 64 + (qpos & 63);
;         mwn[0] = mp[0]; mwn[1] = mp[64];
;       }
;     }
;   };
;   issue_loads(0);
;   f32x16 o[2];
; #pragma unroll
;   for (int d = 0; d < 2; ++d)
; #pragma unroll
;     for (int i = 0; i < 16; ++i) o[d][i] = 0.f;
;   float l = 0.f;
;   const int pr = (l31 & ~12) | ((l31 & 4) << 1) | ((l31 & 8) >> 1);
;   const int swk = MIXA ? ((pr >> 1) & 7) : ((pr >> 2) & 3), swv = (l31 >> 1) & 7;
.LBB0_107:
	s_or_b64 exec, exec, s[18:19]
	v_mad_u64_u32 v[126:127], s[18:19], v0, s33, 0
	v_mul_f32_e32 v0, 0x42828f5c, v12
	v_mad_i32_i24 v127, v1, s33, v127
	v_mul_f32_e32 v0, v11, v0
	v_sub_f32_e32 v1, v47, v13
	v_sub_f32_e32 v11, v48, v13
	v_max3_f32 v1, v1, 0, v11
	v_sub_f32_e32 v11, v44, v13
	v_sub_f32_e32 v12, v45, v13
	v_max3_f32 v1, v1, v11, v12
	v_sub_f32_e32 v11, v42, v13
	v_sub_f32_e32 v12, v43, v13
	v_max3_f32 v1, v1, v11, v12
	v_sub_f32_e32 v11, v38, v13
	v_sub_f32_e32 v12, v39, v13
	v_max3_f32 v1, v1, v11, v12
	v_sub_f32_e32 v11, v40, v13
	v_sub_f32_e32 v12, v41, v13
	v_max3_f32 v1, v1, v11, v12
	v_sub_f32_e32 v11, v36, v13
	v_sub_f32_e32 v12, v37, v13
	v_max3_f32 v1, v1, v11, v12
	v_sub_f32_e32 v11, v32, v13
	v_sub_f32_e32 v12, v33, v13
	v_max3_f32 v1, v1, v11, v12
	v_sub_f32_e32 v11, v31, v13
	v_sub_f32_e32 v12, v13, v13
	v_max3_f32 v1, v1, v11, v12
	v_sub_f32_e32 v11, v28, v13
	v_sub_f32_e32 v12, v29, v13
	v_max3_f32 v1, v1, v11, v12
	v_sub_f32_e32 v11, v26, v13
	v_sub_f32_e32 v12, v27, v13
	v_max3_f32 v1, v1, v11, v12
	v_sub_f32_e32 v11, v24, v13
	v_sub_f32_e32 v12, v25, v13
	v_max3_f32 v1, v1, v11, v12
	v_sub_f32_e32 v11, v22, v13
	v_sub_f32_e32 v12, v23, v13
	v_max3_f32 v1, v1, v11, v12
	v_sub_f32_e32 v11, v20, v13
	v_sub_f32_e32 v12, v21, v13
	v_max3_f32 v1, v1, v11, v12
	v_sub_f32_e32 v11, v18, v13
	v_sub_f32_e32 v12, v19, v13
	v_max3_f32 v1, v1, v11, v12
	v_sub_f32_e32 v11, v16, v13
	v_sub_f32_e32 v12, v17, v13
	v_max3_f32 v1, v1, v11, v12
	v_sub_f32_e32 v11, v14, v13
	v_sub_f32_e32 v12, v15, v13
	v_max3_f32 v1, v1, v11, v12
	v_mul_f32_e32 v128, 0x3fb8aa3b, v1
	v_lshlrev_b32_e32 v1, 1, v10
	v_lshrrev_b32_e32 v11, 1, v10
	v_fmac_f32_e32 v128, 0x3e38aa3b, v0
	v_and_b32_e32 v0, 19, v10
	v_and_b32_e32 v1, 8, v1
	v_and_b32_e32 v12, 4, v11
	v_or3_b32 v0, v1, v0, v12
	v_lshrrev_b32_e32 v1, 1, v0
	v_lshlrev_b32_e32 v155, 7, v0
	v_bitop3_b32 v0, v1, v139, 7 bitop3:0x6c
	v_lshlrev_b32_e32 v157, 4, v0
	v_or_b32_e32 v0, 2, v139
	v_bitop3_b32 v0, v1, v0, 7 bitop3:0x6c
	v_lshlrev_b32_e32 v158, 4, v0
	v_or_b32_e32 v0, 4, v139
	v_bitop3_b32 v0, v1, v0, 7 bitop3:0x6c
	v_lshlrev_b32_e32 v159, 4, v0
	v_or_b32_e32 v0, 6, v139
	v_bfe_u32 v10, v10, 1, 3
	v_bitop3_b32 v0, v1, v0, 7 bitop3:0x6c
	v_lshlrev_b32_e32 v160, 4, v0
	v_bitop3_b32 v0, v139, v10, 4 bitop3:0x36
	v_lshlrev_b32_e32 v151, 4, v0
	v_bitop3_b32 v0, v139, v11, 7 bitop3:0x78
	v_lshlrev_b32_e32 v154, 4, v0
	v_bitop3_b32 v0, v139, v10, 2 bitop3:0x36
	v_lshlrev_b32_e32 v153, 4, v0
	v_bitop3_b32 v0, v139, v10, 6 bitop3:0x36
	v_lshlrev_b32_e32 v152, 4, v0
	v_lshlrev_b32_e32 v0, 5, v139
	v_add_lshl_u32 v1, v50, v51, 2
	v_sub_u32_e32 v0, v0, v1
	v_add_u32_e32 v162, 0xa300, v0
	v_lshlrev_b64 v[0:1], 2, v[6:7]
	v_lshlrev_b32_e32 v6, 12, v49
	v_lshl_add_u64 v[130:131], v[8:9], 2, v[0:1]
	v_add_u32_e32 v0, s86, v46
	v_mov_b32_e32 v1, v137
	s_mov_b64 s[18:19], 0x1b000080
	v_lshl_or_b32 v6, v30, 19, v6
	v_lshl_add_u64 v[0:1], v[0:1], 0, s[18:19]
	v_and_or_b32 v6, v6, s25, v54
	v_mov_b32_e32 v7, v137
	v_lshl_add_u64 v[132:133], v[0:1], 0, v[6:7]
	v_add_u32_e32 v6, v52, v49
	v_mov_b32_e32 v7, 0x40000
	v_lshl_add_u32 v6, v6, 12, v7
	s_movk_i32 s0, 0x8000
	v_and_or_b32 v6, v6, s0, v53
	v_readlane_b32 s0, v253, 17
	s_waitcnt vmcnt(0)
	v_mov_b32_e32 v7, v137
	v_readlane_b32 s1, v253, 18
	v_mov_b32_e32 v125, 0
	v_lshl_add_u64 v[134:135], v[0:1], 0, v[6:7]
	v_lshl_add_u64 v[0:1], s[0:1], 0, v[136:137]
	v_lshlrev_b32_e32 v147, 3, v139
	v_lshlrev_b32_e32 v150, 7, v51
	v_add_u32_e32 v148, -2, v145
	v_mov_b32_e32 v129, v128
	v_sub_f32_e32 v228, 0, v128
	v_sub_f32_e32 v229, 0, v128
	v_sub_f32_e32 v230, 0, v128
	v_sub_f32_e32 v231, 0, v128
	v_sub_f32_e32 v232, 0, v128
	v_sub_f32_e32 v233, 0, v128
	v_sub_f32_e32 v234, 0, v128
	v_sub_f32_e32 v235, 0, v128
	v_sub_f32_e32 v236, 0, v128
	v_sub_f32_e32 v237, 0, v128
	v_sub_f32_e32 v238, 0, v128
	v_sub_f32_e32 v239, 0, v128
	v_sub_f32_e32 v240, 0, v128
	v_sub_f32_e32 v241, 0, v128
	v_sub_f32_e32 v242, 0, v128
	v_sub_f32_e32 v243, 0, v128
	v_lshl_or_b32 v149, v34, 1, 1
	v_lshl_add_u64 v[140:141], v[0:1], 0, v[2:3]
	v_lshl_add_u64 v[142:143], v[0:1], 0, v[4:5]
	s_mov_b32 s22, 0
	s_mov_b64 s[58:59], 0
	v_mov_b32_e32 v0, 0
	v_mov_b32_e32 v1, v125
	v_mov_b32_e32 v2, v125
	v_mov_b32_e32 v3, v125
	v_mov_b32_e32 v4, v125
	v_mov_b32_e32 v5, v125
	v_mov_b32_e32 v6, v125
	v_mov_b32_e32 v7, v125
	v_mov_b32_e32 v8, v125
	v_mov_b32_e32 v9, v125
	v_mov_b32_e32 v10, v125
	v_mov_b32_e32 v11, v125
	v_mov_b32_e32 v12, v125
	v_mov_b32_e32 v13, v125
	v_mov_b32_e32 v14, v125
	v_mov_b32_e32 v15, v125
	v_mov_b32_e32 v16, v125
	v_mov_b32_e32 v17, v125
	v_mov_b32_e32 v18, v125
	v_mov_b32_e32 v19, v125
	v_mov_b32_e32 v20, v125
	v_mov_b32_e32 v21, v125
	v_mov_b32_e32 v22, v125
	v_mov_b32_e32 v23, v125
	v_mov_b32_e32 v24, v125
	v_mov_b32_e32 v25, v125
	v_mov_b32_e32 v26, v125
	v_mov_b32_e32 v27, v125
	v_mov_b32_e32 v28, v125
	v_mov_b32_e32 v29, v125
	v_mov_b32_e32 v30, v125
	v_mov_b32_e32 v31, v125
	s_waitcnt vmcnt(0)
	v_mov_b32_e32 v136, v164
	v_mov_b32_e32 v156, v166
	s_waitcnt lgkmcnt(0)
	s_barrier
	v_readfirstlane_b32 s32, v146
	s_mov_b64 s[36:37], s[74:75]
	s_mov_b64 s[38:39], s[74:75]
	s_add_u32 s76, s74, 0x7f00000
	s_addc_u32 s77, s75, 0
	v_add_u32_e32 v168, v155, v157
	v_add_u32_e32 v170, v155, v158
	v_add_u32_e32 v172, v155, v159
	v_add_u32_e32 v174, v155, v160
	v_add_u32_e32 v245, v150, v154
	v_add_u32_e32 v246, v150, v153
	v_add_u32_e32 v247, v150, v151
	v_add_u32_e32 v248, v150, v152
	s_branch .LBB0_110

; template <int DQK, bool MIXA, bool PIPE>
; DI void attn_item(const Params& P, int layer, char* smem, int b, int h, int qt) {
;     ...
;   auto issue_loads = [&](int kt) __attribute__((always_inline)) {
;     const char* kbp = (const char*)(Kp + (size_t)(kt * 64) * ldk);
;     const char* vbp = (const char*)(VT + kt * 64);
;     char* sk = smem + (kt & 1) * STG_B;
; #pragma unroll
;     for (int i = 0; i < NKI; ++i)
;       __builtin_amdgcn_global_load_lds((const unsigned*)(kbp + koff[i]), (unsigned*)(sk + (w * NKI + i) * 1024), 16, 0, 0);
; #pragma unroll
;     for (int i = 0; i < 2; ++i)
;       __builtin_amdgcn_global_load_lds((const unsigned*)(vbp + voff[i]), (unsigned*)(sk + KTILE_B + (w * 2 + i) * 1024), 16, 0, 0);
;     if (MIXA) {
;       if (kt <= cw) {
;         const unsigned* mp = mask + mask_base(b, cw) + (2 * kt) * 64 + (qpos & 63);
;         mwn[0] = mp[0]; mwn[1] = mp[64];
;       }
;     }
;   };
;   issue_loads(0);
;   f32x16 o[2];
; #pragma unroll
;   for (int d = 0; d < 2; ++d)
; #pragma unroll
;     for (int i = 0; i < 16; ++i) o[d][i] = 0.f;
;   float l = 0.f;
;   const int pr = (l31 & ~12) | ((l31 & 4) << 1) | ((l31 & 8) >> 1);
;   const int swk = MIXA ? ((pr >> 1) & 7) : ((pr >> 2) & 3), swv = (l31 >> 1) & 7;
;   asm volatile("s_waitcnt vmcnt(0)" ::: "memory");
;   __syncthreads();
;   for (int kt = 0; kt < nkt; ++kt) {
;     unsigned mw[2] = {mwn[0], mwn[1]};
;     if (kt + 1 < nkt) issue_loads(kt + 1);
;     const char* Ks = smem + (kt & 1) * STG_B;
;     const char* Vs = Ks + KTILE_B;
;     if (kt <= cw) {
;       const int kc = kt;
;       bf16x8 kf[2][NS];
; #pragma unroll
;       for (int kb = 0; kb < 2; ++kb)
; #pragma unroll
;         for (int s = 0; s < NS; ++s) kf[kb][s] = *(const bf16x8*)(Ks + (32 * kb + pr) * KROWB + (((2 * s + H) ^ swk) << 4));
;       __builtin_amdgcn_sched_barrier(0);
;       f32x16 sacc[2];
; #pragma unroll
;       for (int kb = 0; kb < 2; ++kb)
; #pragma unroll
;         for (int i = 0; i < 16; ++i) sacc[kb][i] = 0.f;
; #pragma unroll
;       for (int s = 0; s < NS; ++s) sacc[0] = __builtin_amdgcn_mfma_f32_32x32x16_bf16(kf[0][s], qf[s], sacc[0], 0, 0, 0);
;       bf16x8 vf[2][2][2];
; #pragma unroll
;       for (int d = 0; d < 2; ++d)
; #pragma unroll
;         for (int kb = 0; kb < 2; ++kb)
; #pragma unroll
;           for (int s2 = 0; s2 < 2; ++s2)
.LBB0_110:
	s_add_i32 s20, s22, 1
	s_movk_i32 s21, 0x5000
	s_add_u32 m0, s21, s32
	v_cmp_lt_i32_e64 s[42:43], s22, v145
	global_load_lds_dwordx4 v140, s[36:37]
	s_add_u32 m0, m0, 0x400
	s_nop 0
	global_load_lds_dwordx4 v142, s[36:37]
	s_add_u32 m0, m0, 0x1c00
	s_nop 0
	global_load_lds_dwordx4 v132, s[38:39]
	s_add_u32 m0, m0, 0x400
	s_nop 0
	global_load_lds_dwordx4 v134, s[38:39]
	s_and_saveexec_b64 s[18:19], s[42:43]
	s_cbranch_execz .LBB0_112
	global_load_dword v156, v130, s[76:77] offset:512
	global_load_dword v136, v130, s[76:77] offset:768
.LBB0_112:
	s_or_b64 exec, exec, s[18:19]
	v_cmp_le_i32_e32 vcc, s22, v145
	s_and_saveexec_b64 s[60:61], vcc
	s_cbranch_execz .Lmixa_o_o109
	ds_read_b128 v[36:39], v168
	ds_read_b128 v[32:35], v168 offset:4096
	ds_read_b128 v[40:43], v170
	ds_read_b128 v[120:123], v170 offset:4096
	ds_read_b128 v[44:47], v172
	ds_read_b128 v[116:119], v172 offset:4096
	ds_read_b128 v[80:83], v174
	ds_read_b128 v[108:111], v174 offset:4096
	s_waitcnt lgkmcnt(0)
	v_mfma_f32_32x32x16_bf16 v[48:63], v[36:39], v[76:79], v[228:243]
	ds_read_b128 v[112:115], v245 offset:8192
	ds_read_b128 v[100:103], v246 offset:8192
	v_mfma_f32_32x32x16_bf16 v[48:63], v[40:43], v[72:75], v[48:63]
	v_mfma_f32_32x32x16_bf16 v[48:63], v[44:47], v[68:71], v[48:63]
	v_mfma_f32_32x32x16_bf16 v[48:63], v[80:83], v[64:67], v[48:63]
	ds_read_b128 v[80:83], v247 offset:8192
	ds_read_b128 v[84:87], v248 offset:8192
	ds_read_b128 v[104:107], v245 offset:12288
	ds_read_b128 v[96:99], v246 offset:12288
	ds_read_b128 v[92:95], v247 offset:12288
	ds_read_b128 v[88:91], v248 offset:12288
	v_cmp_ge_i32_e64 s[44:45], s22, v148
	s_nop 4
	s_cmp_lg_u64 s[44:45], 0
	s_cbranch_scc1 .Lmixa_near_0

; template <int DQK, bool MIXA, bool PIPE>
; DI void attn_item(const Params& P, int layer, char* smem, int b, int h, int qt) {
;     ...
;       auto chunk = [&](int kb, int c) __attribute__((always_inline)) {
;         const int s2 = 1 - (c >> 2), e = 3 - (c & 3);
;         const int r0 = 8 * s2 + 2 * e;
;         if (MIXA && c == 4) mrot[kb] <<= 8;
;         f32x2 xv2 = {sacc[kb][r0], sacc[kb][r0 + 1]};
;         xv2 = xv2 * sl2v - mfixv;
;         if (MIXA) {
;           if (near) {
;             const int kl = 16 * (r0 >> 3) + 8 * H + (r0 & 7);
;             const int rel = kc * 64 + 32 * kb + kl - qpos;
;             xv2.x += biasT[rel + 192];
;             xv2.y += biasT[rel + 193];
;           }
;         }
;         f32x2 p2 = {__builtin_amdgcn_exp2f(xv2.x), __builtin_amdgcn_exp2f(xv2.y)};
;         if (MIXA) {
;           float px = p2.x, py = p2.y;
;           asm volatile("v_add_co_u32 %0, vcc, %0, %0\n\tv_cndmask_b32 %1, 0, %1, vcc" : "+v"(mrot[kb]), "+v"(py) : : "vcc");
;           asm volatile("v_add_co_u32 %0, vcc, %0, %0\n\tv_cndmask_b32 %1, 0, %1, vcc" : "+v"(mrot[kb]), "+v"(px) : : "vcc");
;           p2.x = px; p2.y = py;
;         }
;         ls2 += p2;
;         pkw[kb][s2][e] = pk2(p2.x, p2.y);
;       };
;       {
;         int c0 = 0;
; #pragma unroll
;         for (int s = 0; s < NS; ++s) {
;           sacc[1] = __builtin_amdgcn_mfma_f32_32x32x16_bf16(kf[1][s], qf[s], sacc[1], 0, 0, 0);
;           const int cend = (8 * (s + 1)) / NS;
; #pragma unroll
;           for (int c = 0; c < 8; ++c) if (c >= c0 && c < cend) chunk(0, c);
;           c0 = cend;
;           __builtin_amdgcn_sched_barrier(0);
;         }
;       }
;       bf16x8 pf0[2], pf1[2];
; #pragma unroll
;       for (int s2 = 0; s2 < 2; ++s2) { u32x4 t = {pkw[0][s2][0], pkw[0][s2][1], pkw[0][s2][2], pkw[0][s2][3]}; pf0[s2] = __builtin_bit_cast(bf16x8, t); }
; #pragma unroll
;       for (int j = 0; j < 4; ++j) {
;         const int s2 = j >> 1, d = j & 1;
;         o[d] = __builtin_amdgcn_mfma_f32_32x32x16_bf16(vf[d][0][s2], pf0[s2], o[d], 0, 0, 0);
;         chunk(1, 2 * j); chunk(1, 2 * j + 1);
;         __builtin_amdgcn_sched_barrier(0);
;       }
; #pragma unroll
;       for (int s2 = 0; s2 < 2; ++s2) { u32x4 t = {pkw[1][s2][0], pkw[1][s2][1], pkw[1][s2][2], pkw[1][s2][3]}; pf1[s2] = __builtin_bit_cast(bf16x8, t); }
; #pragma unroll
;       for (int j = 0; j < 4; ++j) {
.Lmixa_near_14:
	ds_read2_b32 v[40:41], v162 offset0:34 offset1:35
	s_waitcnt lgkmcnt(0)
	v_pk_add_f32 v[34:35], v[34:35], v[40:41]
	s_branch .Lmixa_back_14
.Lmixa_o_o108:
	v_add_f32_e32 v40, 0, v62
	v_add_f32_e32 v41, 0, v63
	v_exp_f32_e32 v33, v33
	v_add_f32_e32 v40, v40, v60
	v_add_f32_e32 v41, v41, v61
	v_exp_f32_e32 v32, v32
	v_add_f32_e32 v40, v40, v58
	v_add_f32_e32 v41, v41, v59
	v_add_co_u32 v100, vcc, v100, v100
	v_cndmask_b32 v33, 0, v33, vcc
	s_nop 0
	v_add_f32_e32 v40, v40, v56
	v_add_f32_e32 v41, v41, v57
	v_add_co_u32 v100, vcc, v100, v100
	v_cndmask_b32 v32, 0, v32, vcc
	s_nop 0
	v_add_f32_e32 v40, v40, v54
	v_add_f32_e32 v41, v41, v55
	s_nop 0
	v_add_f32_e32 v40, v40, v52
	v_add_f32_e32 v41, v41, v53
	s_nop 0
	v_add_f32_e32 v40, v40, v116
	v_add_f32_e32 v41, v41, v117
	s_nop 0
	v_add_f32_e32 v40, v40, v118
	v_add_f32_e32 v41, v41, v119
	s_nop 0
	v_add_f32_e32 v40, v40, v46
	v_add_f32_e32 v41, v41, v47
	s_nop 0
	v_add_f32_e32 v40, v40, v44
	v_add_f32_e32 v41, v41, v45
	s_nop 0
	v_add_f32_e32 v40, v40, v48
	v_add_f32_e32 v41, v41, v49
	s_nop 0
	v_add_f32_e32 v40, v40, v50
	v_add_f32_e32 v41, v41, v51
	s_nop 0
	v_add_f32_e32 v40, v40, v38
	v_add_f32_e32 v41, v41, v39
	s_nop 0
	v_add_f32_e32 v40, v40, v36
	v_add_f32_e32 v41, v41, v37
	v_cvt_pk_bf16_f32 v36, v36, v37
	v_add_f32_e32 v42, v40, v34
	v_add_f32_e32 v43, v41, v35
	v_cvt_pk_bf16_f32 v35, v34, v35
	v_cvt_pk_bf16_f32 v37, v38, v39
	v_cvt_pk_bf16_f32 v38, v50, v51
	v_cvt_pk_bf16_f32 v39, v48, v49
	v_cvt_pk_bf16_f32 v40, v44, v45
	v_cvt_pk_bf16_f32 v41, v46, v47
	v_cvt_pk_bf16_f32 v34, v32, v33
	s_nop 1
	v_mfma_f32_32x32x16_bf16 v[0:15], v[80:83], v[34:37], v[0:15]
	v_add_f32_e64 v32, v42, v32
	v_add_f32_e64 v33, v43, v33
	v_add_f32_e32 v32, v32, v33
	v_add_f32_e32 v125, v125, v32
	v_mfma_f32_32x32x16_bf16 v[16:31], v[92:95], v[34:37], v[16:31]
	v_mfma_f32_32x32x16_bf16 v[0:15], v[84:87], v[38:41], v[0:15]
	v_mfma_f32_32x32x16_bf16 v[16:31], v[88:91], v[38:41], v[16:31]

; template <int DQK, bool MIXA, bool PIPE>
; DI void attn_item(const Params& P, int layer, char* smem, int b, int h, int qt) {
;     ...
;   auto issue_loads = [&](int kt) __attribute__((always_inline)) {
;     const char* kbp = (const char*)(Kp + (size_t)(kt * 64) * ldk);
;     const char* vbp = (const char*)(VT + kt * 64);
;     char* sk = smem + (kt & 1) * STG_B;
; #pragma unroll
;     for (int i = 0; i < NKI; ++i)
;       __builtin_amdgcn_global_load_lds((const unsigned*)(kbp + koff[i]), (unsigned*)(sk + (w * NKI + i) * 1024), 16, 0, 0);
; #pragma unroll
;     for (int i = 0; i < 2; ++i)
;       __builtin_amdgcn_global_load_lds((const unsigned*)(vbp + voff[i]), (unsigned*)(sk + KTILE_B + (w * 2 + i) * 1024), 16, 0, 0);
;     if (MIXA) {
;       if (kt <= cw) {
;         const unsigned* mp = mask + mask_base(b, cw) + (2 * kt) * 64 + (qpos & 63);
;         mwn[0] = mp[0]; mwn[1] = mp[64];
;       }
;     }
;   };
;   issue_loads(0);
;   f32x16 o[2];
; #pragma unroll
;   for (int d = 0; d < 2; ++d)
; #pragma unroll
;     for (int i = 0; i < 16; ++i) o[d][i] = 0.f;
;   float l = 0.f;
;   const int pr = (l31 & ~12) | ((l31 & 4) << 1) | ((l31 & 8) >> 1);
;   const int swk = MIXA ? ((pr >> 1) & 7) : ((pr >> 2) & 3), swv = (l31 >> 1) & 7;
;   asm volatile("s_waitcnt vmcnt(0)" ::: "memory");
;   __syncthreads();
;   for (int kt = 0; kt < nkt; ++kt) {
;     unsigned mw[2] = {mwn[0], mwn[1]};
;     if (kt + 1 < nkt) issue_loads(kt + 1);
;     const char* Ks = smem + (kt & 1) * STG_B;
;     const char* Vs = Ks + KTILE_B;
;     if (kt <= cw) {
;       const int kc = kt;
;       bf16x8 kf[2][NS];
; #pragma unroll
;       for (int kb = 0; kb < 2; ++kb)
; #pragma unroll
;         for (int s = 0; s < NS; ++s) kf[kb][s] = *(const bf16x8*)(Ks + (32 * kb + pr) * KROWB + (((2 * s + H) ^ swk) << 4));
;       __builtin_amdgcn_sched_barrier(0);
;       f32x16 sacc[2];
; #pragma unroll
;       for (int kb = 0; kb < 2; ++kb)
; #pragma unroll
;         for (int i = 0; i < 16; ++i) sacc[kb][i] = 0.f;
; #pragma unroll
;       for (int s = 0; s < NS; ++s) sacc[0] = __builtin_amdgcn_mfma_f32_32x32x16_bf16(kf[0][s], qf[s], sacc[0], 0, 0, 0);
;       bf16x8 vf[2][2][2];
; #pragma unroll
;       for (int d = 0; d < 2; ++d)
; #pragma unroll
;         for (int kb = 0; kb < 2; ++kb)
; #pragma unroll
;           for (int s2 = 0; s2 < 2; ++s2)
.Lmixa_o_o110:
	s_add_i32 s20, s22, 1
	s_mov_b32 s21, 0
	s_add_u32 m0, s21, s32
	v_cmp_lt_i32_e64 s[42:43], s22, v145
	global_load_lds_dwordx4 v140, s[36:37]
	s_add_u32 m0, m0, 0x400
	s_nop 0
	global_load_lds_dwordx4 v142, s[36:37]
	s_add_u32 m0, m0, 0x1c00
	s_nop 0
	global_load_lds_dwordx4 v132, s[38:39]
	s_add_u32 m0, m0, 0x400
	s_nop 0
	global_load_lds_dwordx4 v134, s[38:39]
	s_and_saveexec_b64 s[18:19], s[42:43]
	s_cbranch_execz .Lmixa_o_o112
	global_load_dword v156, v130, s[76:77] offset:512
	global_load_dword v136, v130, s[76:77] offset:768
.Lmixa_o_o112:
	s_or_b64 exec, exec, s[18:19]
	v_cmp_le_i32_e32 vcc, s22, v145
	s_and_saveexec_b64 s[60:61], vcc
	s_cbranch_execz .LBB0_109
	ds_read_b128 v[36:39], v168 offset:20480
	ds_read_b128 v[32:35], v168 offset:24576
	ds_read_b128 v[40:43], v170 offset:20480
	ds_read_b128 v[120:123], v170 offset:24576
	ds_read_b128 v[44:47], v172 offset:20480
	ds_read_b128 v[116:119], v172 offset:24576
	ds_read_b128 v[80:83], v174 offset:20480
	ds_read_b128 v[108:111], v174 offset:24576
	s_waitcnt lgkmcnt(0)
	v_mfma_f32_32x32x16_bf16 v[48:63], v[36:39], v[76:79], v[228:243]
	ds_read_b128 v[112:115], v245 offset:28672
	ds_read_b128 v[100:103], v246 offset:28672
	v_mfma_f32_32x32x16_bf16 v[48:63], v[40:43], v[72:75], v[48:63]
	v_mfma_f32_32x32x16_bf16 v[48:63], v[44:47], v[68:71], v[48:63]
	v_mfma_f32_32x32x16_bf16 v[48:63], v[80:83], v[64:67], v[48:63]
	ds_read_b128 v[80:83], v247 offset:28672
	ds_read_b128 v[84:87], v248 offset:28672
	ds_read_b128 v[104:107], v245 offset:32768
	ds_read_b128 v[96:99], v246 offset:32768
	ds_read_b128 v[92:95], v247 offset:32768
	ds_read_b128 v[88:91], v248 offset:32768
	v_cmp_ge_i32_e64 s[44:45], s22, v148
	s_nop 4
	s_cmp_lg_u64 s[44:45], 0
	s_cbranch_scc1 .Lmixa_o_near_0
